# hand-written RET_QKV epilogue: tile-uniform region select on SALU, 16-byte stores with 64-byte row segments
# speedup vs baseline: 1.1365x; 1.0140x over previous
.LBB0_795:
	v_readfirstlane_b32 s100, v178
	s_nop 0
	s_lshr_b32 s100, s100, 6
	s_lshr_b32 s101, s100, 2
	s_and_b32 s100, s100, 3
	s_lshl_b32 s101, s101, 7
	s_add_i32 s101, s101, s61
	s_lshl_b32 s100, s100, 6
	s_movk_i32 s3, 0x3ff
	s_cmpk_lt_u32 s36, 0x800
	s_cselect_b32 s2, 11, 12
	s_cselect_b32 s3, s3, 0x7ff
	s_and_b32 s3, s36, s3
	s_add_i32 s3, s3, s100
	s_lshl_b32 s3, s3, 1
	s_lshr_b32 s4, s36, 10
	s_min_u32 s4, s4, 2
	s_mul_i32 s5, s4, 0x3000000
	s_add_u32 s3, s3, s5
	s_lshl_b32 s5, s101, s2
	s_add_u32 s3, s3, s5
	s_add_u32 s98, s68, s3
	s_addc_u32 s99, s69, 0
	s_lshl_b32 s7, 16, s2
	v_and_b32_e32 v242, 15, v178
	v_bfe_u32 v243, v178, 4, 1
	v_lshlrev_b32_e32 v242, s2, v242
	v_lshl_add_u32 v242, v243, 5, v242
	v_bfe_u32 v243, v178, 5, 1
	s_nop 0
	v_lshl_add_u32 v242, v243, 4, v242
	s_cmp_lg_u32 s4, 1
	s_cbranch_scc1 .Lepi6_noscale
	s_mov_b32 s6, s30
	v_pk_mul_f32 v[124:125], v[124:125], s[6:7] op_sel_hi:[1,0]
	v_pk_mul_f32 v[126:127], v[126:127], s[6:7] op_sel_hi:[1,0]
	v_pk_mul_f32 v[120:121], v[120:121], s[6:7] op_sel_hi:[1,0]
	v_pk_mul_f32 v[122:123], v[122:123], s[6:7] op_sel_hi:[1,0]
	v_pk_mul_f32 v[116:117], v[116:117], s[6:7] op_sel_hi:[1,0]
	v_pk_mul_f32 v[118:119], v[118:119], s[6:7] op_sel_hi:[1,0]
	v_pk_mul_f32 v[112:113], v[112:113], s[6:7] op_sel_hi:[1,0]
	v_pk_mul_f32 v[114:115], v[114:115], s[6:7] op_sel_hi:[1,0]
	v_pk_mul_f32 v[108:109], v[108:109], s[6:7] op_sel_hi:[1,0]
	v_pk_mul_f32 v[110:111], v[110:111], s[6:7] op_sel_hi:[1,0]
	v_pk_mul_f32 v[104:105], v[104:105], s[6:7] op_sel_hi:[1,0]
	v_pk_mul_f32 v[106:107], v[106:107], s[6:7] op_sel_hi:[1,0]
	v_pk_mul_f32 v[100:101], v[100:101], s[6:7] op_sel_hi:[1,0]
	v_pk_mul_f32 v[102:103], v[102:103], s[6:7] op_sel_hi:[1,0]
	v_pk_mul_f32 v[96:97], v[96:97], s[6:7] op_sel_hi:[1,0]
	v_pk_mul_f32 v[98:99], v[98:99], s[6:7] op_sel_hi:[1,0]
	v_pk_mul_f32 v[92:93], v[92:93], s[6:7] op_sel_hi:[1,0]
	v_pk_mul_f32 v[94:95], v[94:95], s[6:7] op_sel_hi:[1,0]
	v_pk_mul_f32 v[88:89], v[88:89], s[6:7] op_sel_hi:[1,0]
	v_pk_mul_f32 v[90:91], v[90:91], s[6:7] op_sel_hi:[1,0]
	v_pk_mul_f32 v[84:85], v[84:85], s[6:7] op_sel_hi:[1,0]
	v_pk_mul_f32 v[86:87], v[86:87], s[6:7] op_sel_hi:[1,0]
	v_pk_mul_f32 v[80:81], v[80:81], s[6:7] op_sel_hi:[1,0]
	v_pk_mul_f32 v[82:83], v[82:83], s[6:7] op_sel_hi:[1,0]
	v_pk_mul_f32 v[76:77], v[76:77], s[6:7] op_sel_hi:[1,0]
	v_pk_mul_f32 v[78:79], v[78:79], s[6:7] op_sel_hi:[1,0]
	v_pk_mul_f32 v[72:73], v[72:73], s[6:7] op_sel_hi:[1,0]
	v_pk_mul_f32 v[74:75], v[74:75], s[6:7] op_sel_hi:[1,0]
	v_pk_mul_f32 v[68:69], v[68:69], s[6:7] op_sel_hi:[1,0]
	v_pk_mul_f32 v[70:71], v[70:71], s[6:7] op_sel_hi:[1,0]
	v_pk_mul_f32 v[64:65], v[64:65], s[6:7] op_sel_hi:[1,0]
	v_pk_mul_f32 v[66:67], v[66:67], s[6:7] op_sel_hi:[1,0]
	v_pk_mul_f32 v[60:61], v[60:61], s[6:7] op_sel_hi:[1,0]
	v_pk_mul_f32 v[62:63], v[62:63], s[6:7] op_sel_hi:[1,0]
	v_pk_mul_f32 v[56:57], v[56:57], s[6:7] op_sel_hi:[1,0]
	v_pk_mul_f32 v[58:59], v[58:59], s[6:7] op_sel_hi:[1,0]
	v_pk_mul_f32 v[52:53], v[52:53], s[6:7] op_sel_hi:[1,0]
	v_pk_mul_f32 v[54:55], v[54:55], s[6:7] op_sel_hi:[1,0]
	v_pk_mul_f32 v[48:49], v[48:49], s[6:7] op_sel_hi:[1,0]
	v_pk_mul_f32 v[50:51], v[50:51], s[6:7] op_sel_hi:[1,0]
	v_pk_mul_f32 v[44:45], v[44:45], s[6:7] op_sel_hi:[1,0]
	v_pk_mul_f32 v[46:47], v[46:47], s[6:7] op_sel_hi:[1,0]
	v_pk_mul_f32 v[40:41], v[40:41], s[6:7] op_sel_hi:[1,0]
	v_pk_mul_f32 v[42:43], v[42:43], s[6:7] op_sel_hi:[1,0]
	v_pk_mul_f32 v[36:37], v[36:37], s[6:7] op_sel_hi:[1,0]
	v_pk_mul_f32 v[38:39], v[38:39], s[6:7] op_sel_hi:[1,0]
	v_pk_mul_f32 v[32:33], v[32:33], s[6:7] op_sel_hi:[1,0]
	v_pk_mul_f32 v[34:35], v[34:35], s[6:7] op_sel_hi:[1,0]
	v_pk_mul_f32 v[28:29], v[28:29], s[6:7] op_sel_hi:[1,0]
	v_pk_mul_f32 v[30:31], v[30:31], s[6:7] op_sel_hi:[1,0]
	v_pk_mul_f32 v[24:25], v[24:25], s[6:7] op_sel_hi:[1,0]
	v_pk_mul_f32 v[26:27], v[26:27], s[6:7] op_sel_hi:[1,0]
	v_pk_mul_f32 v[20:21], v[20:21], s[6:7] op_sel_hi:[1,0]
	v_pk_mul_f32 v[22:23], v[22:23], s[6:7] op_sel_hi:[1,0]
	v_pk_mul_f32 v[16:17], v[16:17], s[6:7] op_sel_hi:[1,0]
	v_pk_mul_f32 v[18:19], v[18:19], s[6:7] op_sel_hi:[1,0]
	v_pk_mul_f32 v[12:13], v[12:13], s[6:7] op_sel_hi:[1,0]
	v_pk_mul_f32 v[14:15], v[14:15], s[6:7] op_sel_hi:[1,0]
	v_pk_mul_f32 v[8:9], v[8:9], s[6:7] op_sel_hi:[1,0]
	v_pk_mul_f32 v[10:11], v[10:11], s[6:7] op_sel_hi:[1,0]
	v_pk_mul_f32 v[4:5], v[4:5], s[6:7] op_sel_hi:[1,0]
	v_pk_mul_f32 v[6:7], v[6:7], s[6:7] op_sel_hi:[1,0]
	v_pk_mul_f32 v[0:1], v[0:1], s[6:7] op_sel_hi:[1,0]
	v_pk_mul_f32 v[2:3], v[2:3], s[6:7] op_sel_hi:[1,0]
.Lepi6_noscale:
	v_cvt_pk_bf16_f32 v124, v124, v125
	v_cvt_pk_bf16_f32 v125, v126, v127
	v_cvt_pk_bf16_f32 v126, v120, v121
	v_cvt_pk_bf16_f32 v127, v122, v123
	v_cvt_pk_bf16_f32 v116, v116, v117
	v_cvt_pk_bf16_f32 v117, v118, v119
	v_cvt_pk_bf16_f32 v118, v112, v113
	v_cvt_pk_bf16_f32 v119, v114, v115
	v_permlane16_swap_b32_e32 v124, v126
	v_permlane16_swap_b32_e32 v125, v127
	v_permlane16_swap_b32_e32 v116, v118
	v_permlane16_swap_b32_e32 v117, v119
	global_store_dwordx4 v242, v[124:127], s[98:99]
	global_store_dwordx4 v242, v[116:119], s[98:99] offset:64
	s_add_u32 s98, s98, s7
	s_addc_u32 s99, s99, 0
	v_cvt_pk_bf16_f32 v108, v108, v109
	v_cvt_pk_bf16_f32 v109, v110, v111
	v_cvt_pk_bf16_f32 v110, v104, v105
	v_cvt_pk_bf16_f32 v111, v106, v107
	v_cvt_pk_bf16_f32 v100, v100, v101
	v_cvt_pk_bf16_f32 v101, v102, v103
	v_cvt_pk_bf16_f32 v102, v96, v97
	v_cvt_pk_bf16_f32 v103, v98, v99
	v_permlane16_swap_b32_e32 v108, v110
	v_permlane16_swap_b32_e32 v109, v111
	v_permlane16_swap_b32_e32 v100, v102
	v_permlane16_swap_b32_e32 v101, v103
	global_store_dwordx4 v242, v[108:111], s[98:99]
	global_store_dwordx4 v242, v[100:103], s[98:99] offset:64
	s_add_u32 s98, s98, s7
	s_addc_u32 s99, s99, 0
	v_cvt_pk_bf16_f32 v92, v92, v93
	v_cvt_pk_bf16_f32 v93, v94, v95
	v_cvt_pk_bf16_f32 v94, v88, v89
	v_cvt_pk_bf16_f32 v95, v90, v91
	v_cvt_pk_bf16_f32 v84, v84, v85
	v_cvt_pk_bf16_f32 v85, v86, v87
	v_cvt_pk_bf16_f32 v86, v80, v81
	v_cvt_pk_bf16_f32 v87, v82, v83
	v_permlane16_swap_b32_e32 v92, v94
	v_permlane16_swap_b32_e32 v93, v95
	v_permlane16_swap_b32_e32 v84, v86
	v_permlane16_swap_b32_e32 v85, v87
	global_store_dwordx4 v242, v[92:95], s[98:99]
	global_store_dwordx4 v242, v[84:87], s[98:99] offset:64
	s_add_u32 s98, s98, s7
	s_addc_u32 s99, s99, 0
	v_cvt_pk_bf16_f32 v76, v76, v77
	v_cvt_pk_bf16_f32 v77, v78, v79
	v_cvt_pk_bf16_f32 v78, v72, v73
	v_cvt_pk_bf16_f32 v79, v74, v75
	v_cvt_pk_bf16_f32 v68, v68, v69
	v_cvt_pk_bf16_f32 v69, v70, v71
	v_cvt_pk_bf16_f32 v70, v64, v65
	v_cvt_pk_bf16_f32 v71, v66, v67
	v_permlane16_swap_b32_e32 v76, v78
	v_permlane16_swap_b32_e32 v77, v79
	v_permlane16_swap_b32_e32 v68, v70
	v_permlane16_swap_b32_e32 v69, v71
	global_store_dwordx4 v242, v[76:79], s[98:99]
	global_store_dwordx4 v242, v[68:71], s[98:99] offset:64
	s_add_u32 s98, s98, s7
	s_addc_u32 s99, s99, 0
	v_cvt_pk_bf16_f32 v60, v60, v61
	v_cvt_pk_bf16_f32 v61, v62, v63
	v_cvt_pk_bf16_f32 v62, v56, v57
	v_cvt_pk_bf16_f32 v63, v58, v59
	v_cvt_pk_bf16_f32 v52, v52, v53
	v_cvt_pk_bf16_f32 v53, v54, v55
	v_cvt_pk_bf16_f32 v54, v48, v49
	v_cvt_pk_bf16_f32 v55, v50, v51
	v_permlane16_swap_b32_e32 v60, v62
	v_permlane16_swap_b32_e32 v61, v63
	v_permlane16_swap_b32_e32 v52, v54
	v_permlane16_swap_b32_e32 v53, v55
	global_store_dwordx4 v242, v[60:63], s[98:99]
	global_store_dwordx4 v242, v[52:55], s[98:99] offset:64
	s_add_u32 s98, s98, s7
	s_addc_u32 s99, s99, 0
	v_cvt_pk_bf16_f32 v44, v44, v45
	v_cvt_pk_bf16_f32 v45, v46, v47
	v_cvt_pk_bf16_f32 v46, v40, v41
	v_cvt_pk_bf16_f32 v47, v42, v43
	v_cvt_pk_bf16_f32 v36, v36, v37
	v_cvt_pk_bf16_f32 v37, v38, v39
	v_cvt_pk_bf16_f32 v38, v32, v33
	v_cvt_pk_bf16_f32 v39, v34, v35
	v_permlane16_swap_b32_e32 v44, v46
	v_permlane16_swap_b32_e32 v45, v47
	v_permlane16_swap_b32_e32 v36, v38
	v_permlane16_swap_b32_e32 v37, v39
	global_store_dwordx4 v242, v[44:47], s[98:99]
	global_store_dwordx4 v242, v[36:39], s[98:99] offset:64
	s_add_u32 s98, s98, s7
	s_addc_u32 s99, s99, 0
	v_cvt_pk_bf16_f32 v28, v28, v29
	v_cvt_pk_bf16_f32 v29, v30, v31
	v_cvt_pk_bf16_f32 v30, v24, v25
	v_cvt_pk_bf16_f32 v31, v26, v27
	v_cvt_pk_bf16_f32 v20, v20, v21
	v_cvt_pk_bf16_f32 v21, v22, v23
	v_cvt_pk_bf16_f32 v22, v16, v17
	v_cvt_pk_bf16_f32 v23, v18, v19
	v_permlane16_swap_b32_e32 v28, v30
	v_permlane16_swap_b32_e32 v29, v31
	v_permlane16_swap_b32_e32 v20, v22
	v_permlane16_swap_b32_e32 v21, v23
	global_store_dwordx4 v242, v[28:31], s[98:99]
	global_store_dwordx4 v242, v[20:23], s[98:99] offset:64
	s_add_u32 s98, s98, s7
	s_addc_u32 s99, s99, 0
	v_cvt_pk_bf16_f32 v12, v12, v13
	v_cvt_pk_bf16_f32 v13, v14, v15
	v_cvt_pk_bf16_f32 v14, v8, v9
	v_cvt_pk_bf16_f32 v15, v10, v11
	v_cvt_pk_bf16_f32 v4, v4, v5
	v_cvt_pk_bf16_f32 v5, v6, v7
	v_cvt_pk_bf16_f32 v6, v0, v1
	v_cvt_pk_bf16_f32 v7, v2, v3
	v_permlane16_swap_b32_e32 v12, v14
	v_permlane16_swap_b32_e32 v13, v15
	v_permlane16_swap_b32_e32 v4, v6
	v_permlane16_swap_b32_e32 v5, v7
	global_store_dwordx4 v242, v[12:15], s[98:99]
	global_store_dwordx4 v242, v[4:7], s[98:99] offset:64
	s_branch .LBB0_780
